# s5_scan spread over all 256 workgroups (128 threads each) instead of 64x512
# speedup vs baseline: 1.0015x; 1.0015x over previous
.LBB0_320:
	s_or_b64 exec, exec, s[4:5]
	s_mov_b64 s[12:13], s[84:85]
	s_waitcnt lgkmcnt(0)
	s_barrier
	v_mbcnt_lo_u32_b32 v0, -1, 0
	v_mbcnt_hi_u32_b32 v0, -1, v0
	s_getreg_b32 s2, hwreg(HW_REG_HW_ID, 0, 6)
	s_lshl_b32 s2, s2, 2
	s_and_b32 s2, s2, 0xfc
	s_add_i32 s2, s2, 0
	s_add_i32 s2, s2, 0x23400
	v_mov_b32_e32 v2, s2
	ds_read_b32 v2, v2
	v_readlane_b32 s3, v255, 2
	s_waitcnt lgkmcnt(0)
	v_readfirstlane_b32 s2, v2
	s_lshr_b32 s3, s3, 2
	s_lshl_b32 s2, s2, 6
	s_cmp_lt_u32 s2, 0x80
	s_cselect_b32 s2, s2, 0x8000
	s_add_i32 s2, s2, s3
	v_add_u32_e32 v3, s2, v0
	s_mov_b32 s2, 0x8000
	v_cmp_gt_i32_e32 vcc, s2, v3
	s_and_saveexec_b64 s[10:11], vcc
	s_cbranch_execz .LBB0_326
	s_load_dwordx2 s[2:3], s[12:13], 0xc8
	s_load_dwordx4 s[4:7], s[12:13], 0xb8
	v_bfe_u32 v4, v3, 6, 6
	v_readlane_b32 s8, v255, 17
	v_and_b32_e32 v2, 63, v0
	v_readlane_b32 s9, v255, 18
	v_or_b32_e32 v0, s8, v4
	s_waitcnt lgkmcnt(0)
	v_lshl_add_u64 v[6:7], v[0:1], 2, s[2:3]
	global_load_dword v5, v[6:7], off
	v_lshlrev_b64 v[6:7], 8, v[0:1]
	v_lshl_or_b32 v6, v2, 2, v6
	v_lshl_add_u64 v[8:9], s[6:7], 0, v[6:7]
	global_load_dword v0, v[8:9], off
	v_lshl_add_u64 v[6:7], s[4:5], 0, v[6:7]
	global_load_dword v7, v[6:7], off
	s_waitcnt vmcnt(2)
	v_mul_f32_e32 v5, 0x3fb8aa3b, v5
	v_exp_f32_e32 v8, v5
	s_waitcnt vmcnt(1)
	v_mul_f32_e32 v0, 0x42000000, v0
	v_mul_f32_e32 v5, v8, v0
	v_and_b32_e32 v6, 0x7fffffff, v5
	v_cmp_nlt_f32_e64 s[2:3], |v5|, s88
	s_and_saveexec_b64 s[4:5], s[2:3]
	s_xor_b64 s[14:15], exec, s[4:5]
	s_cbranch_execz .LBB0_323
	v_lshrrev_b32_e32 v0, 23, v6
	v_add_u32_e32 v0, 0xffffff88, v0
	v_cmp_lt_u32_e32 vcc, 63, v0
	s_nop 1
	v_cndmask_b32_e32 v9, 0, v227, vcc
	v_add_u32_e32 v0, v9, v0
	v_cmp_lt_u32_e64 s[4:5], 31, v0
	s_nop 1
	v_cndmask_b32_e64 v9, 0, v228, s[4:5]
	v_add_u32_e32 v0, v9, v0
	v_cmp_lt_u32_e64 s[6:7], 31, v0
	s_nop 1
	v_cndmask_b32_e64 v9, 0, v228, s[6:7]
	v_add_u32_e32 v9, v9, v0
	v_and_b32_e32 v0, 0x7fffff, v6
	v_or_b32_e32 v22, 0x800000, v0
	v_mad_u64_u32 v[10:11], s[2:3], v22, s89, 0
	v_mov_b32_e32 v0, v11
	v_mad_u64_u32 v[12:13], s[2:3], v22, s90, v[0:1]
	v_mov_b32_e32 v0, v13
	v_mad_u64_u32 v[14:15], s[2:3], v22, s91, v[0:1]
	v_mov_b32_e32 v0, v15
	v_mad_u64_u32 v[16:17], s[2:3], v22, s92, v[0:1]
	v_mov_b32_e32 v0, v17
	v_mad_u64_u32 v[18:19], s[2:3], v22, s93, v[0:1]
	v_mov_b32_e32 v0, v19
	v_mad_u64_u32 v[20:21], s[2:3], v22, s94, v[0:1]
	v_mov_b32_e32 v0, v21
	v_mad_u64_u32 v[22:23], s[2:3], v22, s95, v[0:1]
	v_cndmask_b32_e32 v11, v20, v16, vcc
	v_cndmask_b32_e32 v0, v22, v18, vcc
	v_cndmask_b32_e32 v15, v23, v20, vcc
	v_cndmask_b32_e64 v13, v0, v11, s[4:5]
	v_cndmask_b32_e64 v0, v15, v0, s[4:5]
	v_cndmask_b32_e32 v15, v18, v14, vcc
	v_cndmask_b32_e64 v11, v11, v15, s[4:5]
	v_cndmask_b32_e64 v0, v0, v13, s[6:7]
	v_cndmask_b32_e64 v13, v13, v11, s[6:7]
	v_sub_u32_e32 v17, 32, v9
	v_alignbit_b32 v18, v0, v13, v17
	v_cmp_eq_u32_e64 s[8:9], 0, v9
	v_cndmask_b32_e32 v10, v14, v10, vcc
	s_nop 0
	v_cndmask_b32_e64 v9, v18, v0, s[8:9]
	v_cndmask_b32_e32 v0, v16, v12, vcc
	v_cndmask_b32_e64 v12, v15, v0, s[4:5]
	v_cndmask_b32_e64 v11, v11, v12, s[6:7]
	v_alignbit_b32 v15, v13, v11, v17
	v_cndmask_b32_e64 v13, v15, v13, s[8:9]
	v_bfe_u32 v18, v9, 29, 1
	v_cndmask_b32_e64 v0, v0, v10, s[4:5]
	v_alignbit_b32 v15, v9, v13, 30
	v_sub_u32_e32 v19, 0, v18
	v_cndmask_b32_e64 v0, v12, v0, s[6:7]
	v_xor_b32_e32 v15, v15, v19
	v_alignbit_b32 v10, v11, v0, v17
	v_cndmask_b32_e64 v10, v10, v11, s[8:9]
	v_ffbh_u32_e32 v12, v15
	v_alignbit_b32 v11, v13, v10, 30
	v_min_u32_e32 v12, 32, v12
	v_alignbit_b32 v0, v10, v0, 30
	v_xor_b32_e32 v11, v11, v19
	v_sub_u32_e32 v13, 31, v12
	v_xor_b32_e32 v0, v0, v19
	v_alignbit_b32 v14, v15, v11, v13
	v_alignbit_b32 v0, v11, v0, v13
	v_alignbit_b32 v10, v14, v0, 9
	v_ffbh_u32_e32 v11, v10
	v_min_u32_e32 v11, 32, v11
	v_lshrrev_b32_e32 v16, 29, v9
	v_not_b32_e32 v13, v11
	v_alignbit_b32 v0, v10, v0, v13
	v_lshlrev_b32_e32 v10, 31, v16
	v_or_b32_e32 v13, 0x33000000, v10
	v_add_lshl_u32 v11, v11, v12, 23
	v_lshrrev_b32_e32 v0, 9, v0
	v_sub_u32_e32 v11, v13, v11
	v_or_b32_e32 v10, 0.5, v10
	v_lshlrev_b32_e32 v12, 23, v12
	v_or_b32_e32 v0, v11, v0
	v_lshrrev_b32_e32 v11, 9, v14
	v_sub_u32_e32 v10, v10, v12
	v_or_b32_e32 v10, v11, v10
	v_mul_f32_e32 v11, 0x3fc90fda, v10
	v_fma_f32 v12, v10, s96, -v11
	v_fmac_f32_e32 v12, 0x33a22168, v10
	v_fmac_f32_e32 v12, 0x3fc90fda, v0
	v_lshrrev_b32_e32 v9, 30, v9
	v_add_f32_e32 v0, v11, v12
	v_add_u32_e32 v9, v18, v9
